# v13 plus first key tile of GQA and MLA units no longer drains the second tile's LDS-DMA (vmcnt(0) removed; Q and tile 0 covered by the counted wait ahead of the barrier)
# speedup vs baseline: 1.0026x; 1.0026x over previous
.LBB0_289:
	s_min_u32 s3, s5, 0xc0
	s_lshl_b32 s3, s3, 8
	s_and_b32 s3, s3, 0x300
	s_add_i32 s3, s46, s3
	s_mul_i32 s36, s3, 0x300
	v_readlane_b32 s1, v254, 21
	v_mov_b32_e32 v80, v188
	s_sext_i32_i16 s0, s0
	s_mul_hi_i32 s33, s3, 0x300
	s_add_u32 s36, s1, s36
	v_readlane_b32 s1, v254, 23
	s_waitcnt lgkmcnt(0)
	s_barrier
	s_addc_u32 s41, s1, s33
	v_ashrrev_i32_e32 v62, 3, v80
	s_lshl_b32 s62, s0, 6
	v_add_u32_e32 v4, s10, v62
	s_ashr_i32 s63, s62, 31
	v_lshrrev_b32_e32 v0, 1, v4
	s_lshl_b64 s[46:47], s[62:63], 1
	v_xor_b32_e32 v0, v0, v80
	s_add_u32 s40, s36, s46
	v_lshlrev_b32_e32 v0, 3, v0
	s_addc_u32 s41, s41, s47
	v_and_b32_e32 v121, 31, v80
	v_and_b32_e32 v63, 56, v0
	v_lshlrev_b32_e32 v0, 3, v80
	v_ashrrev_i32_e32 v120, 5, v80
	v_and_b32_e32 v64, 24, v0
	v_or_b32_e32 v2, s51, v121
	v_mov_b64_e32 v[0:1], s[40:41]
	s_movk_i32 s0, 0x300
	v_mad_i64_i32 v[0:1], s[40:41], v2, s0, v[0:1]
	v_lshlrev_b32_e32 v2, 3, v120
	v_ashrrev_i32_e32 v3, 31, v2
	v_lshl_add_u64 v[0:1], v[2:3], 1, v[0:1]
	global_load_dwordx4 v[82:85], v[0:1], off
	global_load_dwordx4 v[86:89], v[0:1], off offset:32
	global_load_dwordx4 v[90:93], v[0:1], off offset:64
	global_load_dwordx4 v[94:97], v[0:1], off offset:96
	v_lshlrev_b32_e32 v1, 5, v80
	v_readlane_b32 s0, v255, 14
	s_or_b32 s36, s2, s37
	v_and_b32_e32 v65, 0xffffff80, v1
	v_or_b32_e32 v1, s0, v64
	s_sub_i32 s0, 0, s2
	s_and_b64 s[40:41], s[44:45], exec
	s_cselect_b32 s40, 0, s0
	s_ashr_i32 s41, s40, 31
	s_lshl_b64 s[40:41], s[40:41], 14
	v_lshl_or_b32 v0, v4, 7, v63
	s_add_u32 s54, s56, s40
	v_add_u32_e32 v2, v1, v65
	s_addc_u32 s55, s57, s41
	v_ashrrev_i32_e32 v1, 31, v0
	s_add_u32 s40, s58, s40
	v_lshlrev_b64 v[58:59], 1, v[0:1]
	v_ashrrev_i32_e32 v3, 31, v2
	s_addc_u32 s41, s59, s41
	v_lshl_add_u64 v[0:1], s[54:55], 0, v[58:59]
	s_mov_b32 s0, m0
	s_mov_b32 m0, s17
	s_nop 0
	global_load_lds_dwordx4 v[0:1], off
	s_mov_b32 m0, s0
	v_lshlrev_b64 v[60:61], 1, v[2:3]
	v_lshl_add_u64 v[0:1], s[40:41], 0, v[60:61]
	s_mov_b32 s0, m0
	s_mov_b32 m0, s38
	s_nop 0
	global_load_lds_dwordx4 v[0:1], off
	s_mov_b32 m0, s0
	s_sub_i32 s0, 1, s2
	s_and_b64 s[40:41], s[44:45], exec
	s_cselect_b32 s40, 1, s0
	s_ashr_i32 s41, s40, 31
	s_lshl_b64 s[40:41], s[40:41], 14
	s_add_u32 s54, s56, s40
	s_addc_u32 s55, s57, s41
	s_add_u32 s40, s58, s40
	s_addc_u32 s41, s59, s41
	v_readlane_b32 s1, v253, 62
	v_lshl_add_u64 v[0:1], s[54:55], 0, v[58:59]
	s_add_i32 s0, s16, s1
	s_mov_b32 s50, m0
	s_mov_b32 m0, s0
	s_nop 0
	global_load_lds_dwordx4 v[0:1], off
	s_mov_b32 m0, s50
	v_lshl_add_u64 v[0:1], s[40:41], 0, v[60:61]
	s_add_i32 s0, s80, s1
	s_mov_b32 s40, m0
	s_mov_b32 m0, s0
	s_nop 0
	global_load_lds_dwordx4 v[0:1], off
	s_mov_b32 m0, s40
	v_lshlrev_b32_e32 v0, 4, v80
	v_and_b32_e32 v0, 0xc0, v0
	v_lshrrev_b32_e32 v4, 1, v80
	v_lshl_or_b32 v32, v120, 8, v0
	v_lshlrev_b32_e32 v0, 1, v80
	v_lshlrev_b32_e32 v122, 7, v121
	v_and_b32_e32 v33, 32, v0
	v_bitop3_b32 v0, v4, v120, 7 bitop3:0x6c
	v_add_u32_e32 v5, 0, v122
	v_lshlrev_b32_e32 v125, 4, v0
	s_waitcnt vmcnt(2)
	s_barrier
	v_add_u32_e32 v6, v5, v125
	ds_read_b128 v[0:3], v6
	ds_read_b128 v[16:19], v6 offset:4096
	v_add_u32_e32 v6, 2, v120
	v_bitop3_b32 v6, v6, v4, 7 bitop3:0x78
	v_lshlrev_b32_e32 v126, 4, v6
	v_add_u32_e32 v6, v5, v126
	ds_read_b128 v[20:23], v6
	ds_read_b128 v[68:71], v6 offset:4096
	v_add_u32_e32 v6, 4, v120
	v_bitop3_b32 v6, v6, v4, 7 bitop3:0x78
	v_lshlrev_b32_e32 v127, 4, v6
	v_add_u32_e32 v6, v5, v127
	ds_read_b128 v[24:27], v6
	ds_read_b128 v[54:57], v6 offset:4096
	v_add_u32_e32 v6, 6, v120
	v_bitop3_b32 v4, v6, v4, 7 bitop3:0x78
	v_lshlrev_b32_e32 v128, 4, v4
	v_add_u32_e32 v4, v5, v128
	ds_read_b128 v[28:31], v4
	ds_read_b128 v[50:53], v4 offset:4096
	s_waitcnt lgkmcnt(0)
	v_mfma_f32_32x32x16_bf16 v[0:15], v[0:3], v[82:85], 0
	v_or3_b32 v129, v32, v33, v64
	s_sub_i32 s0, 2, s2
	s_and_b64 s[44:45], s[44:45], exec
	s_cselect_b32 s44, 2, s0
	s_ashr_i32 s45, s44, 31
	s_lshl_b64 s[44:45], s[44:45], 14
	s_add_u32 s54, s56, s44
	v_mfma_f32_32x32x16_bf16 v[0:15], v[20:23], v[86:89], v[0:15]
	s_addc_u32 s55, s57, s45
	s_add_u32 s44, s58, s44
	v_add_u32_e32 v66, 0, v129
	s_addc_u32 s45, s59, s45
	ds_read_b64_tr_b16 v[46:47], v66 offset:12288
	ds_read_b64_tr_b16 v[48:49], v66 offset:12800
	ds_read_b64_tr_b16 v[42:43], v66 offset:13312
	ds_read_b64_tr_b16 v[44:45], v66 offset:13824
	ds_read_b64_tr_b16 v[38:39], v66 offset:14336
	ds_read_b64_tr_b16 v[40:41], v66 offset:14848
	ds_read_b64_tr_b16 v[34:35], v66 offset:15360
	ds_read_b64_tr_b16 v[36:37], v66 offset:15872
	s_add_i32 s0, s17, 0xa000
	s_mov_b32 s33, 1
	v_mfma_f32_32x32x16_bf16 v[0:15], v[24:27], v[90:93], v[0:15]
	v_cmp_gt_u32_e64 s[40:41], 32, v80
	v_lshl_add_u32 v123, v121, 2, s6
	v_lshl_add_u32 v124, v120, 4, s6
	s_add_i32 s37, s2, s37
	v_mfma_f32_32x32x16_bf16 v[0:15], v[28:31], v[94:97], v[0:15]
	v_mfma_f32_32x32x16_bf16 v[16:31], v[16:19], v[82:85], 0
	s_nop 10
	v_max_f32_e32 v32, v1, v1
	v_max_f32_e32 v33, v0, v0
	v_max_f32_e32 v32, v33, v32
	v_max3_f32 v32, v32, v2, v3
	v_max3_f32 v32, v32, v4, v5
	v_max3_f32 v32, v32, v6, v7
	v_max3_f32 v32, v32, v8, v9
	v_mfma_f32_32x32x16_bf16 v[16:31], v[68:71], v[86:89], v[16:31]
	v_max3_f32 v32, v32, v10, v11
	v_max3_f32 v32, v32, v12, v13
	v_max3_f32 v32, v32, v14, v15
	v_mfma_f32_32x32x16_bf16 v[16:31], v[54:57], v[90:93], v[16:31]
	v_mfma_f32_32x32x16_bf16 v[16:31], v[50:53], v[94:97], v[16:31]
	s_nop 11
	v_max3_f32 v32, v32, v16, v17
	v_max3_f32 v32, v32, v18, v19
	v_max3_f32 v32, v32, v20, v21
	v_max3_f32 v32, v32, v22, v23
	v_max3_f32 v32, v32, v24, v25
	v_max3_f32 v32, v32, v26, v27
	v_max3_f32 v32, v32, v28, v29
	v_max3_f32 v32, v32, v30, v31
	ds_bpermute_b32 v33, v219, v32
	s_waitcnt lgkmcnt(0)
	v_max_f32_e32 v33, v33, v33
	v_max_f32_e32 v32, v32, v33
	v_sub_f32_e32 v16, v16, v32
	v_sub_f32_e32 v0, v0, v32
	v_sub_f32_e32 v17, v17, v32
	v_sub_f32_e32 v1, v1, v32
	v_exp_f32_e32 v69, v0
	v_exp_f32_e32 v70, v16
	v_sub_f32_e32 v18, v18, v32
	v_sub_f32_e32 v2, v2, v32
	v_exp_f32_e32 v71, v1
	v_exp_f32_e32 v72, v17
	v_sub_f32_e32 v19, v19, v32
	v_sub_f32_e32 v3, v3, v32
	v_exp_f32_e32 v73, v2
	v_exp_f32_e32 v74, v18
	v_exp_f32_e32 v75, v3
	v_exp_f32_e32 v76, v19
	v_add_f32_e32 v0, v70, v69
	v_add_f32_e32 v0, 0, v0
	v_add_f32_e32 v1, v72, v71
	v_add_f32_e32 v0, v1, v0
	v_add_f32_e32 v1, v74, v73
	v_sub_f32_e32 v20, v20, v32
	v_sub_f32_e32 v21, v21, v32
	v_sub_f32_e32 v4, v4, v32
	v_sub_f32_e32 v33, v5, v32
	v_add_f32_e32 v0, v1, v0
	v_add_f32_e32 v1, v76, v75
	v_add_f32_e32 v2, v1, v0
	v_exp_f32_e32 v1, v4
	v_exp_f32_e32 v5, v20
	v_exp_f32_e32 v0, v33
	v_exp_f32_e32 v4, v21
	v_sub_f32_e32 v50, v6, v32
	v_sub_f32_e32 v51, v7, v32
	v_sub_f32_e32 v22, v22, v32
	v_pk_add_f32 v[6:7], v[4:5], v[0:1]
	v_sub_f32_e32 v23, v23, v32
	v_add_f32_e32 v7, v7, v2
	v_sub_f32_e32 v54, v10, v32
	v_pk_mov_b32 v[2:3], v[0:1], v[0:1] op_sel:[1,0]
	v_pk_mov_b32 v[0:1], v[4:5], v[4:5] op_sel:[1,0]
	v_add_f32_e32 v10, v6, v7
	v_exp_f32_e32 v5, v50
	v_exp_f32_e32 v7, v22
	v_exp_f32_e32 v4, v51
	v_exp_f32_e32 v6, v23
	v_sub_f32_e32 v52, v8, v32
	v_sub_f32_e32 v53, v9, v32
	v_sub_f32_e32 v24, v24, v32
	v_pk_add_f32 v[8:9], v[6:7], v[4:5]
	v_sub_f32_e32 v25, v25, v32
	v_add_f32_e32 v9, v9, v10
	v_sub_f32_e32 v55, v11, v32
	v_sub_f32_e32 v67, v14, v32
	v_pk_mov_b32 v[10:11], v[4:5], v[4:5] op_sel:[1,0]
	v_pk_mov_b32 v[4:5], v[6:7], v[6:7] op_sel:[1,0]
	v_add_f32_e32 v14, v8, v9
	v_exp_f32_e32 v7, v52
	v_exp_f32_e32 v9, v24
	v_exp_f32_e32 v6, v53
	v_exp_f32_e32 v8, v25
	v_sub_f32_e32 v56, v12, v32
	v_sub_f32_e32 v57, v13, v32
	v_sub_f32_e32 v26, v26, v32
	v_pk_add_f32 v[12:13], v[8:9], v[6:7]
	v_sub_f32_e32 v27, v27, v32
	v_add_f32_e32 v13, v13, v14
	v_sub_f32_e32 v68, v15, v32
	v_add_f32_e32 v18, v12, v13
	v_exp_f32_e32 v13, v54
	v_exp_f32_e32 v15, v26
	v_exp_f32_e32 v12, v55
	v_exp_f32_e32 v14, v27
	v_sub_f32_e32 v28, v28, v32
	v_sub_f32_e32 v29, v29, v32
	v_exp_f32_e32 v19, v28
	v_pk_add_f32 v[16:17], v[14:15], v[12:13]
	v_sub_f32_e32 v30, v30, v32
	v_add_f32_e32 v17, v17, v18
	v_add_f32_e32 v22, v16, v17
	v_exp_f32_e32 v17, v56
	v_exp_f32_e32 v16, v57
	v_exp_f32_e32 v18, v29
	v_sub_f32_e32 v31, v31, v32
	v_pk_mov_b32 v[6:7], v[6:7], v[6:7] op_sel:[1,0]
	v_pk_mov_b32 v[8:9], v[8:9], v[8:9] op_sel:[1,0]
	v_pk_add_f32 v[20:21], v[18:19], v[16:17]
	v_pk_mov_b32 v[24:25], v[18:19], v[18:19] op_sel:[1,0]
	v_add_f32_e32 v21, v21, v22
	v_pk_mov_b32 v[22:23], v[16:17], v[16:17] op_sel:[1,0]
	v_exp_f32_e32 v17, v67
	v_exp_f32_e32 v19, v30
	v_exp_f32_e32 v16, v68
	v_exp_f32_e32 v18, v31
	v_add_f32_e32 v26, v20, v21
	v_pk_mov_b32 v[12:13], v[12:13], v[12:13] op_sel:[1,0]
	v_pk_mov_b32 v[14:15], v[14:15], v[14:15] op_sel:[1,0]
	v_pk_add_f32 v[20:21], v[18:19], v[16:17]
	v_pk_mov_b32 v[28:29], v[18:19], v[18:19] op_sel:[1,0]
	v_add_f32_e32 v21, v21, v26
	v_pk_mov_b32 v[26:27], v[16:17], v[16:17] op_sel:[1,0]
	v_lshl_add_u64 v[16:17], s[54:55], 0, v[58:59]
	s_mov_b32 s50, m0
	s_mov_b32 m0, s0
	s_nop 0
	global_load_lds_dwordx4 v[16:17], off
	s_mov_b32 m0, s50
	v_lshl_add_u64 v[16:17], s[44:45], 0, v[60:61]
	s_add_i32 s0, s38, 0xa000
	s_mov_b32 s44, m0
	s_mov_b32 m0, s0
	s_nop 0
	global_load_lds_dwordx4 v[16:17], off
	s_mov_b32 m0, s44
	v_cvt_pk_bf16_f32 v16, v69, v71
	v_cvt_pk_bf16_f32 v17, v73, v75
	v_cvt_pk_bf16_f32 v18, v2, v3
	v_cvt_pk_bf16_f32 v19, v10, v11
	v_cvt_pk_bf16_f32 v58, v6, v7
	v_cvt_pk_bf16_f32 v59, v12, v13
	v_cvt_pk_bf16_f32 v56, v0, v1
	v_cvt_pk_bf16_f32 v57, v4, v5
	v_cvt_pk_bf16_f32 v50, v8, v9
	v_cvt_pk_bf16_f32 v51, v14, v15
	v_mfma_f32_32x32x16_bf16 v[0:15], v[16:19], v[46:49], 0
	v_cvt_pk_bf16_f32 v60, v22, v23
	v_cvt_pk_bf16_f32 v61, v26, v27
	v_cvt_pk_bf16_f32 v54, v70, v72
	v_cvt_pk_bf16_f32 v55, v74, v76
	v_cvt_pk_bf16_f32 v52, v24, v25
	v_cvt_pk_bf16_f32 v53, v28, v29
	v_add_f32_e32 v33, v20, v21
	v_mfma_f32_32x32x16_bf16 v[0:15], v[58:61], v[42:45], v[0:15]
	v_add_f32_e64 v114, v32, 0
	v_add_f32_e64 v115, v33, 0
	v_readlane_b32 s0, v255, 27
	v_add_f32_e64 v32, -v114, neg(0)
	v_add_f32_e64 v33, -v115, neg(0)
	s_mov_b32 s54, 1
	v_lshlrev_b32_e32 v33, 7, v62
	v_mov_b32_e32 v46, v32
	v_mov_b32_e32 v47, v32
	v_mfma_f32_32x32x16_bf16 v[0:15], v[54:57], v[38:41], v[0:15]
	v_mfma_f32_32x32x16_bf16 v[0:15], v[50:53], v[34:37], v[0:15]
	ds_read_b64_tr_b16 v[20:21], v66 offset:16384
	ds_read_b64_tr_b16 v[22:23], v66 offset:16896
	ds_read_b64_tr_b16 v[34:35], v66 offset:17408
	ds_read_b64_tr_b16 v[36:37], v66 offset:17920
	ds_read_b64_tr_b16 v[38:39], v66 offset:18432
	ds_read_b64_tr_b16 v[40:41], v66 offset:18944
	ds_read_b64_tr_b16 v[42:43], v66 offset:19456
	ds_read_b64_tr_b16 v[44:45], v66 offset:19968
	s_waitcnt lgkmcnt(6)
	v_mfma_f32_32x32x16_bf16 v[16:31], v[16:19], v[20:23], 0
	s_waitcnt lgkmcnt(4)
	v_mfma_f32_32x32x16_bf16 v[16:31], v[58:61], v[34:37], v[16:31]
	v_add3_u32 v34, s0, v65, v64
	v_ashrrev_i32_e32 v35, 31, v34
	v_mov_b64_e32 v[36:37], 0xc000
	v_lshl_add_u64 v[116:117], v[34:35], 1, v[36:37]
	v_add3_u32 v34, s16, v33, v63
	v_ashrrev_i32_e32 v35, 31, v34
	v_lshl_add_u64 v[118:119], v[34:35], 1, v[36:37]
	s_waitcnt lgkmcnt(2)
	v_mfma_f32_32x32x16_bf16 v[16:31], v[54:57], v[38:41], v[16:31]
	v_mov_b32_e32 v33, v32
	v_mov_b32_e32 v34, v32
	v_mov_b32_e32 v35, v32
	v_mov_b32_e32 v36, v32
	v_mov_b32_e32 v37, v32
	v_mov_b32_e32 v38, v32
	v_mov_b32_e32 v39, v32
	s_waitcnt lgkmcnt(0)
	v_mfma_f32_32x32x16_bf16 v[16:31], v[50:53], v[42:45], v[16:31]
	v_mov_b32_e32 v40, v32
	v_mov_b32_e32 v41, v32
	v_mov_b32_e32 v42, v32
	v_mov_b32_e32 v43, v32
	v_mov_b32_e32 v44, v32
	v_mov_b32_e32 v45, v32
	s_add_i32 s50, s54, 1
	s_cmp_ge_u32 s50, s36
	s_mov_b64 s[44:45], -1
	s_cbranch_scc0 .LBB0_292
	s_branch .LBB0_291

.LBB0_340:
	s_min_i32 s0, s5, 0x60
	s_lshl_b32 s0, s0, 8
	s_and_b32 s0, s0, 0x300
	s_add_i32 s5, s58, s0
	s_mul_i32 s11, s5, 0x480
	v_readlane_b32 s1, v254, 28
	s_mul_hi_i32 s0, s5, 0x480
	s_add_u32 s33, s1, s11
	v_readlane_b32 s1, v254, 30
	s_mul_i32 s40, s2, 0x60
	s_addc_u32 s0, s1, s0
	s_ashr_i32 s41, s40, 31
	s_lshl_b64 s[40:41], s[40:41], 1
	s_add_u32 s40, s33, s40
	v_mov_b32_e32 v80, v188
	s_addc_u32 s41, s0, s41
	s_waitcnt lgkmcnt(0)
	s_barrier
	v_readlane_b32 s0, v255, 19
	v_and_b32_e32 v131, 31, v80
	v_ashrrev_i32_e32 v76, 2, v80
	v_ashrrev_i32_e32 v130, 5, v80
	v_add_u32_e32 v6, s0, v76
	v_or_b32_e32 v4, s51, v131
	v_mov_b64_e32 v[2:3], s[40:41]
	s_movk_i32 s0, 0x480
	v_mad_i64_i32 v[2:3], s[40:41], v4, s0, v[2:3]
	v_lshlrev_b32_e32 v4, 3, v130
	v_ashrrev_i32_e32 v5, 31, v4
	v_lshl_add_u64 v[2:3], v[4:5], 1, v[2:3]
	global_load_dwordx4 v[82:85], v[2:3], off
	global_load_dwordx4 v[86:89], v[2:3], off offset:32
	global_load_dwordx4 v[90:93], v[2:3], off offset:64
	global_load_dwordx4 v[94:97], v[2:3], off offset:96
	global_load_dwordx4 v[98:101], v[2:3], off offset:128
	global_load_dwordx4 v[102:105], v[2:3], off offset:160
	v_ashrrev_i32_e32 v74, 3, v80
	v_add_u32_e32 v1, s10, v74
	v_lshrrev_b32_e32 v0, 1, v1
	v_xor_b32_e32 v0, v0, v80
	v_lshlrev_b32_e32 v0, 3, v0
	v_ashrrev_i32_e32 v7, 4, v80
	v_and_b32_e32 v75, 56, v0
	v_xor_b32_e32 v0, v7, v80
	v_lshlrev_b32_e32 v0, 3, v0
	v_and_b32_e32 v78, 24, v0
	v_lshlrev_b32_e32 v0, 3, v80
	v_and_b32_e32 v77, 24, v0
	s_movk_i32 s50, 0x300
	v_or_b32_e32 v0, s81, v77
	s_or_b32 s33, s3, s36
	v_mul_lo_u32 v1, v1, s50
	s_sub_i32 s0, 0, s3
	v_or_b32_e32 v2, v75, v1
	v_mad_u64_u32 v[0:1], s[40:41], v6, s50, v[0:1]
	s_and_b64 s[40:41], s[28:29], exec
	s_cselect_b32 s40, 0, s0
	s_ashr_i32 s41, s40, 31
	s_mul_i32 s37, s40, 0x18000
	s_mul_hi_i32 s0, s40, 0x18000
	s_add_u32 s54, s48, s37
	s_addc_u32 s55, s49, s0
	s_add_u32 s58, s52, s37
	v_lshl_or_b32 v4, v6, 5, v78
	s_addc_u32 s59, s53, s0
	v_ashrrev_i32_e32 v3, 31, v2
	s_lshl_b64 s[40:41], s[40:41], 12
	v_lshlrev_b64 v[68:69], 1, v[2:3]
	s_add_u32 s40, s56, s40
	v_ashrrev_i32_e32 v5, 31, v4
	v_lshl_add_u64 v[2:3], s[54:55], 0, v[68:69]
	s_mov_b32 s0, m0
	s_mov_b32 m0, s17
	s_nop 0
	global_load_lds_dwordx4 v[2:3], off
	s_mov_b32 m0, s0
	s_addc_u32 s41, s57, s41
	v_lshlrev_b64 v[70:71], 1, v[4:5]
	v_ashrrev_i32_e32 v1, 31, v0
	v_lshl_add_u64 v[2:3], s[40:41], 0, v[70:71]
	s_mov_b32 s0, m0
	s_mov_b32 m0, s7
	s_nop 0
	global_load_lds_dwordx4 v[2:3], off
	s_mov_b32 m0, s0
	v_lshlrev_b64 v[72:73], 1, v[0:1]
	v_lshl_add_u64 v[0:1], s[58:59], 0, v[72:73]
	s_mov_b32 s0, m0
	s_mov_b32 m0, s38
	s_nop 0
	global_load_lds_dwordx4 v[0:1], off
	s_mov_b32 m0, s0
	s_sub_i32 s0, 1, s3
	s_and_b64 s[40:41], s[28:29], exec
	s_cselect_b32 s40, 1, s0
	s_ashr_i32 s41, s40, 31
	s_mul_i32 s37, s40, 0x18000
	s_mul_hi_i32 s0, s40, 0x18000
	s_add_u32 s54, s48, s37
	s_addc_u32 s55, s49, s0
	s_add_u32 s58, s52, s37
	v_readlane_b32 s1, v253, 62
	s_addc_u32 s59, s53, s0
	s_add_i32 s0, s16, s1
	s_lshl_b64 s[40:41], s[40:41], 12
	s_add_u32 s40, s56, s40
	v_lshl_add_u64 v[0:1], s[54:55], 0, v[68:69]
	s_addc_u32 s41, s57, s41
	s_mov_b32 s37, m0
	s_mov_b32 m0, s0
	s_nop 0
	global_load_lds_dwordx4 v[0:1], off
	s_mov_b32 m0, s37
	v_readlane_b32 s0, v255, 20
	v_lshl_add_u64 v[0:1], s[40:41], 0, v[70:71]
	s_addk_i32 s0, 0x7000
	s_mov_b32 s37, m0
	s_mov_b32 m0, s0
	s_nop 0
	global_load_lds_dwordx4 v[0:1], off
	s_mov_b32 m0, s37
	v_lshl_add_u64 v[0:1], s[58:59], 0, v[72:73]
	s_add_i32 s0, s80, s1
	s_mov_b32 s37, m0
	s_mov_b32 m0, s0
	s_nop 0
	global_load_lds_dwordx4 v[0:1], off
	s_mov_b32 m0, s37
	v_lshlrev_b32_e32 v0, 4, v80
	v_and_b32_e32 v0, 0xc0, v0
	v_lshrrev_b32_e32 v4, 1, v80
	v_lshl_or_b32 v40, v130, 8, v0
	v_lshlrev_b32_e32 v0, 5, v7
	v_lshlrev_b32_e32 v132, 7, v131
	v_and_b32_e32 v41, 32, v0
	v_bitop3_b32 v0, v4, v130, 7 bitop3:0x6c
	v_add_u32_e32 v5, 0, v132
	v_lshlrev_b32_e32 v136, 4, v0
	s_waitcnt vmcnt(3)
	s_barrier
	v_add_u32_e32 v6, v5, v136
	ds_read_b128 v[0:3], v6
	ds_read_b128 v[16:19], v6 offset:4096
	v_add_u32_e32 v6, 2, v130
	v_bitop3_b32 v7, v6, v4, 7 bitop3:0x78
	v_lshlrev_b32_e32 v137, 4, v7
	v_add_u32_e32 v7, v5, v137
	ds_read_b128 v[20:23], v7
	ds_read_b128 v[56:59], v7 offset:4096
	v_add_u32_e32 v7, 4, v130
	v_bitop3_b32 v7, v7, v4, 7 bitop3:0x78
	v_lshlrev_b32_e32 v138, 4, v7
	v_add_u32_e32 v7, v5, v138
	ds_read_b128 v[24:27], v7
	ds_read_b128 v[64:67], v7 offset:4096
	v_add_u32_e32 v7, 6, v130
	v_bitop3_b32 v4, v7, v4, 7 bitop3:0x78
	v_lshlrev_b32_e32 v139, 4, v4
	v_lshlrev_b32_e32 v133, 6, v131
	v_add_u32_e32 v4, v5, v139
	ds_read_b128 v[28:31], v4
	ds_read_b128 v[60:63], v4 offset:4096
	v_sub_u32_e32 v4, v5, v133
	v_bitop3_b32 v5, v76, v130, 3 bitop3:0x6c
	v_lshlrev_b32_e32 v140, 4, v5
	v_add_u32_e32 v5, v4, v140
	ds_read_b128 v[32:35], v5 offset:8192
	ds_read_b128 v[52:55], v5 offset:10240
	v_bitop3_b32 v5, v6, v76, 3 bitop3:0x78
	v_lshlrev_b32_e32 v141, 4, v5
	v_add_u32_e32 v4, v4, v141
	ds_read_b128 v[36:39], v4 offset:8192
	ds_read_b128 v[48:51], v4 offset:10240
	s_waitcnt lgkmcnt(0)
	v_mfma_f32_32x32x16_bf16 v[0:15], v[0:3], v[82:85], 0
	s_sub_i32 s0, 2, s3
	s_and_b64 s[28:29], s[28:29], exec
	s_cselect_b32 s28, 2, s0
	s_ashr_i32 s29, s28, 31
	s_mul_i32 s37, s28, 0x18000
	s_mul_hi_i32 s0, s28, 0x18000
	s_add_u32 s54, s48, s37
	v_mfma_f32_32x32x16_bf16 v[0:15], v[20:23], v[86:89], v[0:15]
	s_addc_u32 s55, s49, s0
	s_add_u32 s58, s52, s37
	s_addc_u32 s59, s53, s0
	s_add_i32 s0, s17, 0xa000
	s_lshl_b64 s[28:29], s[28:29], 12
	v_or3_b32 v142, v40, v41, v77
	s_add_u32 s28, s56, s28
	v_mfma_f32_32x32x16_bf16 v[0:15], v[24:27], v[90:93], v[0:15]
	v_add_u32_e32 v79, 0, v142
	s_addc_u32 s29, s57, s29
	s_mov_b32 s11, 1
	v_cmp_gt_u32_e64 s[40:41], 32, v80
	v_lshl_add_u32 v134, v131, 2, s6
	v_lshl_add_u32 v135, v130, 4, s6
	s_add_i32 s36, s3, s36
	v_mfma_f32_32x32x16_bf16 v[0:15], v[28:31], v[94:97], v[0:15]
	v_mfma_f32_32x32x16_bf16 v[16:31], v[16:19], v[82:85], 0
	v_mfma_f32_32x32x16_bf16 v[16:31], v[56:59], v[86:89], v[16:31]
	v_mfma_f32_32x32x16_bf16 v[16:31], v[64:67], v[90:93], v[16:31]
	v_mfma_f32_32x32x16_bf16 v[0:15], v[32:35], v[98:101], v[0:15]
	v_mfma_f32_32x32x16_bf16 v[16:31], v[60:63], v[94:97], v[16:31]
	v_mfma_f32_32x32x16_bf16 v[0:15], v[36:39], v[102:105], v[0:15]
	ds_read_b64_tr_b16 v[44:45], v79 offset:12288
	ds_read_b64_tr_b16 v[46:47], v79 offset:12800
	ds_read_b64_tr_b16 v[40:41], v79 offset:13312
	ds_read_b64_tr_b16 v[42:43], v79 offset:13824
	ds_read_b64_tr_b16 v[36:37], v79 offset:14336
	ds_read_b64_tr_b16 v[38:39], v79 offset:14848
	ds_read_b64_tr_b16 v[32:33], v79 offset:15360
	ds_read_b64_tr_b16 v[34:35], v79 offset:15872
	v_mfma_f32_32x32x16_bf16 v[16:31], v[52:55], v[98:101], v[16:31]
	v_mfma_f32_32x32x16_bf16 v[16:31], v[48:51], v[102:105], v[16:31]
	s_nop 1
	v_max_f32_e32 v48, v1, v1
	v_max_f32_e32 v49, v0, v0
	v_max_f32_e32 v48, v49, v48
	v_max3_f32 v48, v48, v2, v3
	v_max3_f32 v48, v48, v4, v5
	v_max3_f32 v48, v48, v6, v7
	v_max3_f32 v48, v48, v8, v9
	v_max3_f32 v48, v48, v10, v11
	v_max3_f32 v48, v48, v12, v13
	v_max3_f32 v48, v48, v14, v15
	v_max3_f32 v48, v48, v16, v17
	v_max3_f32 v48, v48, v18, v19
	v_max3_f32 v48, v48, v20, v21
	v_max3_f32 v48, v48, v22, v23
	v_max3_f32 v48, v48, v24, v25
	v_max3_f32 v48, v48, v26, v27
	v_max3_f32 v48, v48, v28, v29
	v_max3_f32 v48, v48, v30, v31
	ds_bpermute_b32 v49, v219, v48
	s_waitcnt lgkmcnt(0)
	v_max_f32_e32 v49, v49, v49
	v_max_f32_e32 v48, v48, v49
	v_sub_f32_e32 v16, v16, v48
	v_sub_f32_e32 v0, v0, v48
	v_sub_f32_e32 v17, v17, v48
	v_sub_f32_e32 v1, v1, v48
	v_exp_f32_e32 v60, v0
	v_exp_f32_e32 v61, v16
	v_sub_f32_e32 v18, v18, v48
	v_sub_f32_e32 v2, v2, v48
	v_exp_f32_e32 v62, v1
	v_exp_f32_e32 v63, v17
	v_sub_f32_e32 v19, v19, v48
	v_sub_f32_e32 v3, v3, v48
	v_exp_f32_e32 v64, v2
	v_exp_f32_e32 v65, v18
	v_exp_f32_e32 v66, v3
	v_exp_f32_e32 v67, v19
	v_add_f32_e32 v0, v61, v60
	v_add_f32_e32 v0, 0, v0
	v_add_f32_e32 v1, v63, v62
	v_add_f32_e32 v0, v1, v0
	v_add_f32_e32 v1, v65, v64
	v_sub_f32_e32 v20, v20, v48
	v_sub_f32_e32 v21, v21, v48
	v_sub_f32_e32 v49, v30, v48
	v_sub_f32_e32 v4, v4, v48
	v_sub_f32_e32 v30, v5, v48
	v_add_f32_e32 v0, v1, v0
	v_add_f32_e32 v1, v67, v66
	v_add_f32_e32 v2, v1, v0
	v_exp_f32_e32 v1, v4
	v_exp_f32_e32 v5, v20
	v_exp_f32_e32 v0, v30
	v_exp_f32_e32 v4, v21
	v_sub_f32_e32 v50, v31, v48
	v_sub_f32_e32 v31, v6, v48
	v_sub_f32_e32 v51, v7, v48
	v_pk_add_f32 v[6:7], v[4:5], v[0:1]
	v_sub_f32_e32 v22, v22, v48
	v_sub_f32_e32 v23, v23, v48
	v_add_f32_e32 v7, v7, v2
	v_sub_f32_e32 v54, v10, v48
	v_pk_mov_b32 v[2:3], v[0:1], v[0:1] op_sel:[1,0]
	v_pk_mov_b32 v[0:1], v[4:5], v[4:5] op_sel:[1,0]
	v_add_f32_e32 v10, v6, v7
	v_exp_f32_e32 v5, v31
	v_exp_f32_e32 v7, v22
	v_exp_f32_e32 v4, v51
	v_exp_f32_e32 v6, v23
	v_sub_f32_e32 v52, v8, v48
	v_sub_f32_e32 v53, v9, v48
	v_sub_f32_e32 v24, v24, v48
	v_pk_add_f32 v[8:9], v[6:7], v[4:5]
	v_sub_f32_e32 v25, v25, v48
	v_add_f32_e32 v9, v9, v10
	v_sub_f32_e32 v55, v11, v48
	v_sub_f32_e32 v58, v14, v48
	v_pk_mov_b32 v[10:11], v[4:5], v[4:5] op_sel:[1,0]
	v_pk_mov_b32 v[4:5], v[6:7], v[6:7] op_sel:[1,0]
	v_add_f32_e32 v14, v8, v9
	v_exp_f32_e32 v7, v52
	v_exp_f32_e32 v9, v24
	v_exp_f32_e32 v6, v53
	v_exp_f32_e32 v8, v25
	v_sub_f32_e32 v56, v12, v48
	v_sub_f32_e32 v57, v13, v48
	v_sub_f32_e32 v26, v26, v48
	v_pk_add_f32 v[12:13], v[8:9], v[6:7]
	v_sub_f32_e32 v27, v27, v48
	v_add_f32_e32 v13, v13, v14
	v_sub_f32_e32 v59, v15, v48
	v_add_f32_e32 v18, v12, v13
	v_exp_f32_e32 v13, v54
	v_exp_f32_e32 v15, v26
	v_exp_f32_e32 v12, v55
	v_exp_f32_e32 v14, v27
	v_sub_f32_e32 v28, v28, v48
	v_sub_f32_e32 v29, v29, v48
	v_exp_f32_e32 v19, v28
	v_pk_add_f32 v[16:17], v[14:15], v[12:13]
	v_cvt_pk_bf16_f32 v51, v10, v11
	v_add_f32_e32 v17, v17, v18
	v_add_f32_e32 v22, v16, v17
	v_exp_f32_e32 v17, v56
	v_exp_f32_e32 v16, v57
	v_exp_f32_e32 v18, v29
	v_pk_mov_b32 v[6:7], v[6:7], v[6:7] op_sel:[1,0]
	v_pk_mov_b32 v[8:9], v[8:9], v[8:9] op_sel:[1,0]
	v_pk_mov_b32 v[12:13], v[12:13], v[12:13] op_sel:[1,0]
	v_pk_add_f32 v[20:21], v[18:19], v[16:17]
	v_pk_mov_b32 v[30:31], v[18:19], v[18:19] op_sel:[1,0]
	v_add_f32_e32 v21, v21, v22
	v_pk_mov_b32 v[22:23], v[16:17], v[16:17] op_sel:[1,0]
	v_exp_f32_e32 v17, v58
	v_exp_f32_e32 v19, v49
	v_exp_f32_e32 v16, v59
	v_exp_f32_e32 v18, v50
	v_add_f32_e32 v24, v20, v21
	v_cvt_pk_bf16_f32 v50, v2, v3
	v_pk_mov_b32 v[14:15], v[14:15], v[14:15] op_sel:[1,0]
	v_pk_add_f32 v[20:21], v[18:19], v[16:17]
	v_pk_mov_b32 v[52:53], v[18:19], v[18:19] op_sel:[1,0]
	v_add_f32_e32 v21, v21, v24
	v_add_f32_e32 v49, v20, v21
	v_pk_add_f32 v[122:123], v[48:49], 0 op_sel_hi:[1,0]
	v_cvt_pk_bf16_f32 v48, v60, v62
	v_cvt_pk_bf16_f32 v49, v64, v66
	v_lshl_add_u64 v[18:19], s[54:55], 0, v[68:69]
	s_mov_b32 s37, m0
	s_mov_b32 m0, s0
	s_nop 0
	global_load_lds_dwordx4 v[18:19], off
	s_mov_b32 m0, s37
	v_lshl_add_u64 v[18:19], s[28:29], 0, v[70:71]
	v_pk_mov_b32 v[24:25], v[16:17], v[16:17] op_sel:[1,0]
	s_add_i32 s0, s7, 0xa000
	s_mov_b32 s28, m0
	s_mov_b32 m0, s0
	s_nop 0
	global_load_lds_dwordx4 v[18:19], off
	s_mov_b32 m0, s28
	v_lshl_add_u64 v[18:19], s[58:59], 0, v[72:73]
	s_add_i32 s0, s38, 0xa000
	s_mov_b32 s28, m0
	s_mov_b32 m0, s0
	s_nop 0
	global_load_lds_dwordx4 v[18:19], off
	s_mov_b32 m0, s28
	v_cvt_pk_bf16_f32 v26, v6, v7
	v_cvt_pk_bf16_f32 v27, v12, v13
	v_cvt_pk_bf16_f32 v29, v24, v25
	v_cvt_pk_bf16_f32 v24, v0, v1
	v_cvt_pk_bf16_f32 v25, v4, v5
	v_cvt_pk_bf16_f32 v18, v8, v9
	v_cvt_pk_bf16_f32 v19, v14, v15
	v_mfma_f32_32x32x16_bf16 v[0:15], v[48:51], v[44:47], 0
	v_cvt_pk_bf16_f32 v28, v22, v23
	v_cvt_pk_bf16_f32 v22, v61, v63
	v_cvt_pk_bf16_f32 v23, v65, v67
	v_cvt_pk_bf16_f32 v20, v30, v31
	v_cvt_pk_bf16_f32 v21, v52, v53
	v_pk_add_f32 v[16:17], v[122:123], 0 neg_lo:[1,1] neg_hi:[1,1]
	v_readlane_b32 s0, v255, 29
	v_mfma_f32_32x32x16_bf16 v[0:15], v[26:29], v[40:43], v[0:15]
	v_lshlrev_b32_e32 v17, 5, v76
	v_mfma_f32_32x32x16_bf16 v[0:15], v[22:25], v[36:39], v[0:15]
	v_mfma_f32_32x32x16_bf16 v[0:15], v[18:21], v[32:35], v[0:15]
	ds_read_b64_tr_b16 v[30:31], v79 offset:16384
	ds_read_b64_tr_b16 v[32:33], v79 offset:16896
	ds_read_b64_tr_b16 v[52:53], v79 offset:17408
	ds_read_b64_tr_b16 v[54:55], v79 offset:17920
	ds_read_b64_tr_b16 v[56:57], v79 offset:18432
	ds_read_b64_tr_b16 v[58:59], v79 offset:18944
	ds_read_b64_tr_b16 v[60:61], v79 offset:19456
	ds_read_b64_tr_b16 v[62:63], v79 offset:19968
	s_waitcnt lgkmcnt(6)
	v_mfma_f32_32x32x16_bf16 v[32:47], v[48:51], v[30:33], 0
	v_mov_b32_e32 v30, v16
	v_mov_b32_e32 v31, v16
	s_waitcnt lgkmcnt(4)
	v_mfma_f32_32x32x16_bf16 v[32:47], v[26:29], v[52:55], v[32:47]
	v_mov_b32_e32 v26, v16
	v_mov_b32_e32 v27, v16
	v_mov_b32_e32 v28, v16
	v_mov_b32_e32 v29, v16
	s_waitcnt lgkmcnt(2)
	v_mfma_f32_32x32x16_bf16 v[32:47], v[22:25], v[56:59], v[32:47]
	v_mov_b32_e32 v22, v16
	v_mov_b32_e32 v23, v16
	v_mov_b32_e32 v24, v16
	v_mov_b32_e32 v25, v16
	s_waitcnt lgkmcnt(0)
	v_mfma_f32_32x32x16_bf16 v[32:47], v[18:21], v[60:63], v[32:47]
	v_add3_u32 v18, s0, v17, v78
	v_ashrrev_i32_e32 v19, 31, v18
	v_mov_b64_e32 v[20:21], 0x3000
	v_mul_lo_u32 v17, v76, s50
	v_readlane_b32 s0, v255, 30
	v_lshl_add_u64 v[124:125], v[18:19], 1, v[20:21]
	v_mov_b32_e32 v20, v16
	v_add3_u32 v18, s0, v17, v77
	v_ashrrev_i32_e32 v19, 31, v18
	v_mul_lo_u32 v17, v74, s50
	s_mul_i32 s0, s73, 0x1800
	v_lshl_add_u64 v[126:127], v[18:19], 1, v[186:187]
	v_add3_u32 v18, s0, v17, v75
	v_ashrrev_i32_e32 v19, 31, v18
	v_lshl_add_u64 v[128:129], v[18:19], 1, v[186:187]
	s_mov_b32 s50, 1
	v_mov_b32_e32 v17, v16
	v_mov_b32_e32 v18, v16
	v_mov_b32_e32 v19, v16
	v_mov_b32_e32 v21, v16
	s_add_i32 s37, s50, 1
	s_cmp_ge_u32 s37, s33
	s_mov_b64 s[28:29], -1
	s_cbranch_scc0 .LBB0_343
	s_branch .LBB0_342
